# GLA scan: gate section B1 hand-written with packed f32 + 4-token partial sums, group-sum pass and its barrier removed (section C builds totals/prefix from the partial sums), loop-invariant addresses h
# speedup vs baseline: 1.0106x; 1.0014x over previous
; #define OPAQUE_TID(name) int name = MK_TID; asm volatile("" : "+v"(name))
; __device__ __forceinline__ void scan_unit(const int unit, const Args& a, unsigned char* lds, const int mk_wid) {
;     ...
;     { const int l_ = MK_TID & 63, r32 = l_ & 31, hi = l_ >> 5; const float* up = a.in[dir ? 12 : 10] + (size_t)(8 * hi) * 512 + h * 128 + (wid & 3) * 32 + r32;
;       v4u w; w.x = pk2(up[0], up[512]); w.y = pk2(up[2 * 512], up[3 * 512]); w.z = pk2(up[4 * 512], up[5 * 512]); w.w = pk2(up[6 * 512], up[7 * 512]);
;       upf = __builtin_bit_cast(bf16x8, w); biasc = a.in[dir ? 13 : 11][h * 128 + (wid & 3) * 32 + r32]; }
;     u16* qe = (u16*)(lds + L_QE); u16* ke = (u16*)(lds + L_KE); u16* am = (u16*)(lds + L_AM);
;     float* las = (float*)(lds + L_LAS); float* gs = (float*)(lds + L_GS); float* dl = (float*)(lds + L_DL);
;     const int ldsb = (int)(uintptr_t)lds;
;     u16* ot = (u16*)(lds + L_LAS);
;     int pend_cc = -1;
;     ...
;     f32x16 S[4]; S[0] = f32x16{}; S[1] = f32x16{}; S[2] = f32x16{}; S[3] = f32x16{};
;     bf16x8 qraw[2], kraw[2], vraw[4]; bf16x8 lraw = bf16x8{};
;     ...
;     GLA_LOAD(0);
;     ...
;         { OPAQUE_TID(t_); const int c = t_ & 127, g = t_ >> 7;
;           float bl[16]; float run = 0.f;
;           { const float* lp = las + (g * 16) * 128 + c;
; #pragma unroll
;             for (int ii = 0; ii < 16; ++ii) { run += lp[ii * 128]; bl[ii] = run; } }
;           gs[g * 128 + c] = run;
;           __syncthreads();
;           const float g0 = gs[c], g1 = gs[128 + c], g2 = gs[256 + c], g3 = gs[384 + c];
;           const float off = (g > 0 ? g0 : 0.f) + (g > 1 ? g1 : 0.f) + (g > 2 ? g2 : 0.f);
;           const float btot = (g0 + g1) + (g2 + g3);
;           const float dlc = __builtin_amdgcn_exp2f(btot * 1.4426950408889634f);
;           if (g == 0) dl[c] = dlc;
;           u16* qcol = qe + (g * 16) * QP + c; u16* kcol = ke + (g * 16) * QP + c; unsigned char* kdb = lds + L_KD + v_st(g * 16, c);
; #pragma unroll
;           for (int ii = 0; ii < 16; ++ii) { const float bb = bl[ii] + off;
;               const float qf = bf2f(qcol[ii * QP]), kf = bf2f(kcol[ii * QP]);
;               const float e = __builtin_amdgcn_exp2f(bb * 1.4426950408889634f), ker = kf * __builtin_amdgcn_rcpf(e);
;               qcol[ii * QP] = f2bf(qf * (0.088388347648318440f * e));
;               kcol[ii * QP] = f2bf(ker);
;               *(u16*)(kdb + v_st(ii, 0)) = f2bf(ker * dlc); } }
.Lscan_qk_done2:
	v_mov_b32_e32 v128, 0
	v_mov_b32_e32 v129, 0
	v_mov_b32_e32 v130, 0
	v_mov_b32_e32 v131, 0
	v_mov_b32_e32 v132, 0
	v_mov_b32_e32 v133, 0
	v_mov_b32_e32 v134, 0
	v_mov_b32_e32 v135, 0
	v_mbcnt_lo_u32_b32 v66, -1, 0
	v_mbcnt_hi_u32_b32 v66, -1, v66
	v_bfe_u32 v67, v66, 4, 1
	v_lshlrev_b32_e32 v67, 3, v67
	v_bfe_u32 v68, v66, 2, 2
	v_add_u32_e32 v67, v67, v68
	s_and_b32 s96, s70, 3
	s_lshl_b32 s96, s96, 4
	v_add_u32_e32 v67, s96, v67
	v_lshrrev_b32_e32 v68, 5, v66
	v_lshlrev_b32_e32 v68, 6, v68
	v_and_b32_e32 v69, 3, v66
	v_lshl_add_u32 v68, v69, 4, v68
	s_lshr_b32 s96, s70, 2
	s_lshl_b32 s96, s96, 8
	v_add_u32_e32 v68, s96, v68
	v_sub_u32_e32 v69, 63, v67
	v_cndmask_b32_e64 v69, v69, v67, s[2:3]
	v_add_u32_e32 v69, s12, v69
	v_lshl_add_u32 v247, v69, 11, v68
	v_add_u32_e32 v248, 0x80, v247
	v_add_u32_e32 v67, 4, v67
	v_sub_u32_e32 v69, 63, v67
	v_cndmask_b32_e64 v69, v69, v67, s[2:3]
	v_add_u32_e32 v69, s12, v69
	v_lshl_add_u32 v249, v69, 11, v68
	v_add_u32_e32 v250, 0x80, v249
	v_mbcnt_lo_u32_b32 v66, -1, 0
	v_mbcnt_hi_u32_b32 v66, -1, v66
	s_lshr_b32 s96, s70, 2
	s_lshl_b32 s96, s96, 5
	v_and_b32_e32 v67, 31, v66
	v_add_u32_e32 v67, s96, v67
	v_sub_u32_e32 v68, 63, v67
	v_cndmask_b32_e64 v67, v68, v67, s[2:3]
	v_add_u32_e32 v67, s12, v67
	v_bfe_u32 v68, v66, 5, 1
	v_lshlrev_b32_e32 v68, 4, v68
	v_lshl_add_u32 v251, v67, 6, v68
	s_bitcmp1_b32 s8, 0
	s_cselect_b32 s97, 3, 0
	s_lshl_b32 s97, s97, 12
	v_add_u32_e32 v70, s97, v251
	v_mov_b32_e32 v71, 0
	v_lshl_add_u64 v[70:71], v[152:153], 0, v[70:71]
	global_load_dwordx4 v[96:99], v[70:71], off
	v_lshrrev_b32_e32 v67, 3, v66
	v_add_u32_e32 v67, s96, v67
	v_and_b32_e32 v68, 7, v66
	v_lshlrev_b32_e32 v68, 4, v68
	s_and_b32 s97, s70, 3
	s_lshl_b32 s97, s97, 7
	v_add_u32_e32 v68, s97, v68
	v_lshl_add_u32 v253, v67, 9, v68
	v_add_u32_e32 v253, s9, v253
	v_sub_u32_e32 v69, 63, v67
	v_cndmask_b32_e64 v67, v69, v67, s[2:3]
	v_lshl_add_u32 v252, v67, 11, v68
	v_mbcnt_lo_u32_b32 v64, -1, 0
	v_mbcnt_hi_u32_b32 v64, -1, v64
	s_cmp_gt_u32 s70, 0
	s_cselect_b32 s97, 1.0, 0
	v_mov_b32_e32 v238, s97
	s_cmp_gt_u32 s70, 1
	s_cselect_b32 s97, 1.0, 0
	v_mov_b32_e32 v239, s97
	s_cmp_gt_u32 s70, 2
	s_cselect_b32 s97, 1.0, 0
	v_mov_b32_e32 v240, s97
	s_cmp_gt_u32 s70, 3
	s_cselect_b32 s97, 1.0, 0
	v_mov_b32_e32 v241, s97
	s_cmp_gt_u32 s70, 4
	s_cselect_b32 s97, 1.0, 0
	v_mov_b32_e32 v242, s97
	s_cmp_gt_u32 s70, 5
	s_cselect_b32 s97, 1.0, 0
	v_mov_b32_e32 v243, s97
	s_cmp_gt_u32 s70, 6
	s_cselect_b32 s97, 1.0, 0
	v_mov_b32_e32 v244, s97
	s_mul_i32 s99, s70, 0x880
	v_and_b32_e32 v66, 2, v64
	v_lshlrev_b32_e32 v66, 1, v66
	v_and_b32_e32 v67, 4, v64
	v_lshrrev_b32_e32 v67, 1, v67
	v_and_b32_e32 v70, 0xfffffff9, v64
	v_or3_b32 v66, v66, v67, v70
	v_lshl_add_u32 v254, v66, 2, s99
	s_lshr_b32 s98, s70, 1
	s_lshl_b32 s98, s98, 12
	s_and_b32 s99, s70, 1
	s_lshl_b32 s99, s99, 8
	s_add_i32 s98, s98, s99
	v_lshrrev_b32_e32 v66, 4, v64
	v_lshlrev_b32_e32 v66, 9, v66
	v_and_b32_e32 v70, 15, v64
	v_lshl_add_u32 v66, v70, 2, v66
	v_add_u32_e32 v255, s98, v66
	s_lshr_b32 s98, s70, 2
	s_lshl_b32 s98, s98, 12
	s_and_b32 s99, s70, 3
	s_lshl_b32 s99, s99, 7
	s_add_i32 s98, s98, s99
	s_add_i32 s98, s98, 0x20000
	v_lshrrev_b32_e32 v66, 5, v64
	v_lshlrev_b32_e32 v66, 9, v66
	v_and_b32_e32 v70, 31, v64
	v_lshl_add_u32 v66, v70, 2, v66
	v_add_u32_e32 v169, s98, v66

; __device__ __forceinline__ int crow(int r, int hi) { return (r & 3) + 8 * (r >> 2) + 4 * hi; }
; __device__ __forceinline__ void scan_unit(const int unit, const Args& a, unsigned char* lds, const int mk_wid) {
;     ...
;           const bf16x8 af = *(const bf16x8*)(lds + L_LR + (tt * 32 + r32) * 32 + hi * 16);
;           const f32x16 z = __builtin_amdgcn_mfma_f32_32x32x16_bf16(af, upf, f32x16{}, 0, 0, 0);
;           float* lw = las + (tt * 32 + 4 * hi) * 128 + ct * 32 + r32;
; #pragma unroll
;           for (int r = 0; r < 16; ++r) { const float zz = z[r] + biasc;
;               lw[crow(r, 0) * 128] = (fminf(zz, 0.f) - __builtin_amdgcn_logf(1.f + __builtin_amdgcn_exp2f(-1.4426950408889634f * fabsf(zz))) * 0.6931471805599453f) * (1.f / 16.f); } }
;     ...
;           { const float* lp = las + (g * 16) * 128 + c;
; #pragma unroll
;             for (int ii = 0; ii < 16; ++ii) { run += lp[ii * 128]; bl[ii] = run; } }
;           gs[g * 128 + c] = run;
.Lscan_noflush:
	v_mbcnt_lo_u32_b32 v64, -1, 0
	v_mbcnt_hi_u32_b32 v64, -1, v64
	s_nop 0
	v_add_u32_e32 v64, s72, v64
	s_nop 0
	v_and_b32_e32 v68, 31, v64
	v_bfe_u32 v69, v64, 5, 1
	v_lshlrev_b32_e32 v69, 11, v69
	v_lshlrev_b32_e32 v68, 2, v68
	v_add3_u32 v80, s45, v69, v68
	v_mfma_f32_32x32x16_bf16 v[64:79], v[96:99], v[108:111], 0
	s_mov_b32 s96, 1.0
	s_mov_b32 s97, 0xbf317218
	s_mov_b32 s98, 0x3db8aa3b
	s_nop 11
	v_pk_add_f32 v[64:65], v[64:65], v[156:157] op_sel_hi:[1,0]
	v_pk_add_f32 v[66:67], v[66:67], v[156:157] op_sel_hi:[1,0]
	v_pk_add_f32 v[68:69], v[68:69], v[156:157] op_sel_hi:[1,0]
	v_pk_add_f32 v[70:71], v[70:71], v[156:157] op_sel_hi:[1,0]
	v_mul_f32_e64 v82, |v64|, s54
	v_mul_f32_e64 v83, |v65|, s54
	v_mul_f32_e64 v84, |v66|, s54
	v_mul_f32_e64 v85, |v67|, s54
	v_mul_f32_e64 v86, |v68|, s54
	v_mul_f32_e64 v87, |v69|, s54
	v_mul_f32_e64 v88, |v70|, s54
	v_mul_f32_e64 v89, |v71|, s54
	v_exp_f32_e32 v82, v82
	v_exp_f32_e32 v83, v83
	v_exp_f32_e32 v84, v84
	v_exp_f32_e32 v85, v85
	v_exp_f32_e32 v86, v86
	v_exp_f32_e32 v87, v87
	v_exp_f32_e32 v88, v88
	v_exp_f32_e32 v89, v89
	v_pk_add_f32 v[82:83], v[82:83], s[96:97] op_sel_hi:[1,0]
	v_pk_add_f32 v[84:85], v[84:85], s[96:97] op_sel_hi:[1,0]
	v_pk_add_f32 v[86:87], v[86:87], s[96:97] op_sel_hi:[1,0]
	v_pk_add_f32 v[88:89], v[88:89], s[96:97] op_sel_hi:[1,0]
	v_log_f32_e32 v82, v82
	v_log_f32_e32 v83, v83
	v_log_f32_e32 v84, v84
	v_log_f32_e32 v85, v85
	v_log_f32_e32 v86, v86
	v_log_f32_e32 v87, v87
	v_log_f32_e32 v88, v88
	v_log_f32_e32 v89, v89
	v_min_f32_e32 v64, 0, v64
	v_min_f32_e32 v65, 0, v65
	v_min_f32_e32 v66, 0, v66
	v_min_f32_e32 v67, 0, v67
	v_min_f32_e32 v68, 0, v68
	v_min_f32_e32 v69, 0, v69
	v_min_f32_e32 v70, 0, v70
	v_min_f32_e32 v71, 0, v71
	v_pk_fma_f32 v[64:65], v[82:83], s[96:97], v[64:65] op_sel:[0,1,0] op_sel_hi:[1,1,1]
	v_pk_fma_f32 v[66:67], v[84:85], s[96:97], v[66:67] op_sel:[0,1,0] op_sel_hi:[1,1,1]
	v_pk_fma_f32 v[68:69], v[86:87], s[96:97], v[68:69] op_sel:[0,1,0] op_sel_hi:[1,1,1]
	v_pk_fma_f32 v[70:71], v[88:89], s[96:97], v[70:71] op_sel:[0,1,0] op_sel_hi:[1,1,1]
	v_pk_mul_f32 v[64:65], v[64:65], s[98:99] op_sel_hi:[1,0]
	v_pk_mul_f32 v[66:67], v[66:67], s[98:99] op_sel_hi:[1,0]
	v_pk_mul_f32 v[68:69], v[68:69], s[98:99] op_sel_hi:[1,0]
	v_pk_mul_f32 v[70:71], v[70:71], s[98:99] op_sel_hi:[1,0]
	ds_write2st64_b32 v80, v64, v65 offset1:2
	ds_write2st64_b32 v80, v66, v67 offset0:4 offset1:6
	ds_write2st64_b32 v80, v68, v69 offset0:16 offset1:18
	ds_write2st64_b32 v80, v70, v71 offset0:20 offset1:22
	v_pk_add_f32 v[72:73], v[72:73], v[156:157] op_sel_hi:[1,0]
	v_pk_add_f32 v[74:75], v[74:75], v[156:157] op_sel_hi:[1,0]
	v_pk_add_f32 v[76:77], v[76:77], v[156:157] op_sel_hi:[1,0]
	v_pk_add_f32 v[78:79], v[78:79], v[156:157] op_sel_hi:[1,0]
	v_mul_f32_e64 v82, |v72|, s54
	v_mul_f32_e64 v83, |v73|, s54
	v_mul_f32_e64 v84, |v74|, s54
	v_mul_f32_e64 v85, |v75|, s54
	v_mul_f32_e64 v86, |v76|, s54
	v_mul_f32_e64 v87, |v77|, s54
	v_mul_f32_e64 v88, |v78|, s54
	v_mul_f32_e64 v89, |v79|, s54
	v_exp_f32_e32 v82, v82
	v_exp_f32_e32 v83, v83
	v_exp_f32_e32 v84, v84
	v_exp_f32_e32 v85, v85
	v_exp_f32_e32 v86, v86
	v_exp_f32_e32 v87, v87
	v_exp_f32_e32 v88, v88
	v_exp_f32_e32 v89, v89
	v_pk_add_f32 v[82:83], v[82:83], s[96:97] op_sel_hi:[1,0]
	v_pk_add_f32 v[84:85], v[84:85], s[96:97] op_sel_hi:[1,0]
	v_pk_add_f32 v[86:87], v[86:87], s[96:97] op_sel_hi:[1,0]
	v_pk_add_f32 v[88:89], v[88:89], s[96:97] op_sel_hi:[1,0]
	v_log_f32_e32 v82, v82
	v_log_f32_e32 v83, v83
	v_log_f32_e32 v84, v84
	v_log_f32_e32 v85, v85
	v_log_f32_e32 v86, v86
	v_log_f32_e32 v87, v87
	v_log_f32_e32 v88, v88
	v_log_f32_e32 v89, v89
	v_min_f32_e32 v72, 0, v72
	v_min_f32_e32 v73, 0, v73
	v_min_f32_e32 v74, 0, v74
	v_min_f32_e32 v75, 0, v75
	v_min_f32_e32 v76, 0, v76
	v_min_f32_e32 v77, 0, v77
	v_min_f32_e32 v78, 0, v78
	v_min_f32_e32 v79, 0, v79
	v_pk_fma_f32 v[72:73], v[82:83], s[96:97], v[72:73] op_sel:[0,1,0] op_sel_hi:[1,1,1]
	v_pk_fma_f32 v[74:75], v[84:85], s[96:97], v[74:75] op_sel:[0,1,0] op_sel_hi:[1,1,1]
	v_pk_fma_f32 v[76:77], v[86:87], s[96:97], v[76:77] op_sel:[0,1,0] op_sel_hi:[1,1,1]
	v_pk_fma_f32 v[78:79], v[88:89], s[96:97], v[78:79] op_sel:[0,1,0] op_sel_hi:[1,1,1]
	v_pk_mul_f32 v[72:73], v[72:73], s[98:99] op_sel_hi:[1,0]
	v_pk_mul_f32 v[74:75], v[74:75], s[98:99] op_sel_hi:[1,0]
	v_pk_mul_f32 v[76:77], v[76:77], s[98:99] op_sel_hi:[1,0]
	v_pk_mul_f32 v[78:79], v[78:79], s[98:99] op_sel_hi:[1,0]
	ds_write2st64_b32 v80, v72, v73 offset0:32 offset1:34
	ds_write2st64_b32 v80, v74, v75 offset0:36 offset1:38
	ds_write2st64_b32 v80, v76, v77 offset0:48 offset1:50
	ds_write2st64_b32 v80, v78, v79 offset0:52 offset1:54
	v_pk_add_f32 v[82:83], v[64:65], v[66:67]
	v_pk_add_f32 v[84:85], v[68:69], v[70:71]
	v_pk_add_f32 v[86:87], v[72:73], v[74:75]
	v_pk_add_f32 v[88:89], v[76:77], v[78:79]
	v_add_f32_e32 v82, v82, v83
	v_add_f32_e32 v84, v84, v85
	v_add_f32_e32 v86, v86, v87
	v_add_f32_e32 v88, v88, v89
	ds_write2st64_b32 v169, v82, v84 offset1:4
	ds_write2st64_b32 v169, v86, v88 offset0:8 offset1:12
	s_waitcnt lgkmcnt(0)
	s_barrier
; __device__ __forceinline__ int v_st(int k, int c) { const int kk = (k & ~0xC) | ((k & 4) << 1) | ((k & 8) >> 1); return ((kk >> 3) * 4 + (c >> 5)) * 512 + ((kk & 7) * 32 + (c & 31)) * 2; }
; __device__ __forceinline__ float bf2f(short s) { return __uint_as_float(((unsigned)(unsigned short)s) << 16); }
; __device__ __forceinline__ float bf2f(u16 u) { return __uint_as_float((unsigned)u << 16); }
; #define OPAQUE_TID(name) int name = MK_TID; asm volatile("" : "+v"(name))
; __device__ __forceinline__ void scan_unit(const int unit, const Args& a, unsigned char* lds, const int mk_wid) {
;     ...
;         { OPAQUE_TID(t_); const int c = t_ & 127, g = t_ >> 7;
;           float bl[16]; float run = 0.f;
;           { const float* lp = las + (g * 16) * 128 + c;
; #pragma unroll
;             for (int ii = 0; ii < 16; ++ii) { run += lp[ii * 128]; bl[ii] = run; } }
;           gs[g * 128 + c] = run;
;           __syncthreads();
;           const float g0 = gs[c], g1 = gs[128 + c], g2 = gs[256 + c], g3 = gs[384 + c];
;           const float off = (g > 0 ? g0 : 0.f) + (g > 1 ? g1 : 0.f) + (g > 2 ? g2 : 0.f);
;           const float btot = (g0 + g1) + (g2 + g3);
;           const float dlc = __builtin_amdgcn_exp2f(btot * 1.4426950408889634f);
;           if (g == 0) dl[c] = dlc;
;           u16* qcol = qe + (g * 16) * QP + c; u16* kcol = ke + (g * 16) * QP + c; unsigned char* kdb = lds + L_KD + v_st(g * 16, c);
; #pragma unroll
;           for (int ii = 0; ii < 16; ++ii) { const float bb = bl[ii] + off;
;               const float qf = bf2f(qcol[ii * QP]), kf = bf2f(kcol[ii * QP]);
;               const float e = __builtin_amdgcn_exp2f(bb * 1.4426950408889634f), ker = kf * __builtin_amdgcn_rcpf(e);
	v_mbcnt_lo_u32_b32 v64, -1, 0
	v_mbcnt_hi_u32_b32 v64, -1, v64
	s_lshl_b32 s96, s70, 12
	s_add_i32 s96, s96, s9
	v_lshl_add_u32 v65, v64, 3, s96
	v_lshlrev_b32_e32 v67, 3, v64
	v_add_u32_e32 v67, 0x20000, v67
	ds_read2st64_b64 v[186:189], v67 offset1:1
	ds_read2st64_b64 v[190:193], v67 offset0:2 offset1:3
	ds_read2st64_b64 v[194:197], v67 offset0:4 offset1:5
	ds_read2st64_b64 v[198:201], v67 offset0:6 offset1:7
	ds_read2st64_b64 v[202:205], v67 offset0:8 offset1:9
	ds_read2st64_b64 v[206:209], v67 offset0:10 offset1:11
	ds_read2st64_b64 v[210:213], v67 offset0:12 offset1:13
	ds_read2st64_b64 v[214:217], v67 offset0:14 offset1:15
	ds_read2st64_b64 v[170:173], v65 offset1:1
	ds_read2st64_b64 v[174:177], v65 offset0:2 offset1:3
	ds_read2st64_b64 v[178:181], v65 offset0:4 offset1:5
	ds_read2st64_b64 v[182:185], v65 offset0:6 offset1:7
	s_waitcnt lgkmcnt(4)
	v_pk_add_f32 v[72:73], v[186:187], v[188:189]
	v_pk_add_f32 v[74:75], v[190:191], v[192:193]
	v_pk_add_f32 v[76:77], v[194:195], v[196:197]
	v_pk_add_f32 v[78:79], v[198:199], v[200:201]
	v_pk_add_f32 v[80:81], v[202:203], v[204:205]
	v_pk_add_f32 v[82:83], v[206:207], v[208:209]
	v_pk_add_f32 v[84:85], v[210:211], v[212:213]
	v_pk_add_f32 v[86:87], v[214:215], v[216:217]
	v_pk_mul_f32 v[88:89], v[238:239], v[72:73] op_sel:[0,0] op_sel_hi:[0,1]
	v_pk_fma_f32 v[88:89], v[238:239], v[74:75], v[88:89] op_sel:[1,0,0] op_sel_hi:[1,1,1]
	v_pk_fma_f32 v[88:89], v[240:241], v[76:77], v[88:89] op_sel:[0,0,0] op_sel_hi:[0,1,1]
	v_pk_fma_f32 v[88:89], v[240:241], v[78:79], v[88:89] op_sel:[1,0,0] op_sel_hi:[1,1,1]
	v_pk_fma_f32 v[88:89], v[242:243], v[80:81], v[88:89] op_sel:[0,0,0] op_sel_hi:[0,1,1]
	v_pk_fma_f32 v[88:89], v[242:243], v[82:83], v[88:89] op_sel:[1,0,0] op_sel_hi:[1,1,1]
	v_pk_fma_f32 v[88:89], v[244:245], v[84:85], v[88:89] op_sel:[0,0,0] op_sel_hi:[0,1,1]
	v_pk_add_f32 v[90:91], v[72:73], v[74:75]
	v_pk_add_f32 v[90:91], v[90:91], v[76:77]
	v_pk_add_f32 v[90:91], v[90:91], v[78:79]
	v_pk_add_f32 v[90:91], v[90:91], v[80:81]
	v_pk_add_f32 v[90:91], v[90:91], v[82:83]
	v_pk_add_f32 v[90:91], v[90:91], v[84:85]
	v_pk_add_f32 v[90:91], v[90:91], v[86:87]
	v_mov_b64_e32 v[92:93], v[90:91]
	v_exp_f32_e32 v92, v92
	v_exp_f32_e32 v93, v93
	s_waitcnt lgkmcnt(0)
	v_pk_add_f32 v[170:171], v[170:171], v[88:89]
	v_pk_add_f32 v[172:173], v[172:173], v[170:171]
	v_pk_add_f32 v[174:175], v[174:175], v[172:173]
	v_pk_add_f32 v[176:177], v[176:177], v[174:175]
	v_pk_add_f32 v[178:179], v[178:179], v[176:177]
	v_pk_add_f32 v[180:181], v[180:181], v[178:179]
	v_pk_add_f32 v[182:183], v[182:183], v[180:181]
	v_pk_add_f32 v[184:185], v[184:185], v[182:183]
	v_exp_f32_e32 v170, v170
	v_exp_f32_e32 v171, v171
	v_exp_f32_e32 v172, v172
	v_exp_f32_e32 v173, v173
	v_exp_f32_e32 v174, v174
	v_exp_f32_e32 v175, v175
	v_exp_f32_e32 v176, v176
	v_exp_f32_e32 v177, v177
	v_exp_f32_e32 v178, v178
	v_exp_f32_e32 v179, v179
	v_exp_f32_e32 v180, v180
	v_exp_f32_e32 v181, v181
	v_exp_f32_e32 v182, v182
	v_exp_f32_e32 v183, v183
	v_exp_f32_e32 v184, v184
	v_exp_f32_e32 v185, v185
	v_rcp_f32_e32 v186, v170
	v_rcp_f32_e32 v187, v171
	v_rcp_f32_e32 v188, v172
	v_rcp_f32_e32 v189, v173
	v_rcp_f32_e32 v190, v174
	v_rcp_f32_e32 v191, v175
	v_rcp_f32_e32 v192, v176
	v_rcp_f32_e32 v193, v177
	v_rcp_f32_e32 v194, v178
	v_rcp_f32_e32 v195, v179
	v_rcp_f32_e32 v196, v180
	v_rcp_f32_e32 v197, v181
	v_rcp_f32_e32 v198, v182
	v_rcp_f32_e32 v199, v183
	v_rcp_f32_e32 v200, v184
	v_rcp_f32_e32 v201, v185
	s_mov_b32 s96, 0x3db504f3
	s_mov_b32 s97, s96
	v_pk_mul_f32 v[170:171], v[170:171], s[96:97]
	v_pk_mul_f32 v[172:173], v[172:173], s[96:97]
	v_pk_mul_f32 v[174:175], v[174:175], s[96:97]
	v_pk_mul_f32 v[176:177], v[176:177], s[96:97]
	v_pk_mul_f32 v[178:179], v[178:179], s[96:97]
	v_pk_mul_f32 v[180:181], v[180:181], s[96:97]
	v_pk_mul_f32 v[182:183], v[182:183], s[96:97]
	v_pk_mul_f32 v[184:185], v[184:185], s[96:97]
	s_cmp_lg_u32 s70, 0
	s_cbranch_scc1 .Lscan_c2_nodl
	v_lshlrev_b32_e32 v70, 3, v64
	v_add_u32_e32 v70, 0x1fc00, v70
	ds_write_b64 v70, v[92:93]
; __device__ __forceinline__ int v_st(int k, int c) { const int kk = (k & ~0xC) | ((k & 4) << 1) | ((k & 8) >> 1); return ((kk >> 3) * 4 + (c >> 5)) * 512 + ((kk & 7) * 32 + (c & 31)) * 2; }
; __device__ __forceinline__ float bf2f(short s) { return __uint_as_float(((unsigned)(unsigned short)s) << 16); }
; __device__ __forceinline__ float bf2f(u16 u) { return __uint_as_float((unsigned)u << 16); }
; __device__ __forceinline__ u16 f2bf(float f) { return (u16)(pk2(f, 0.f) & 0xffffu); }
; __device__ __forceinline__ void scan_unit(const int unit, const Args& a, unsigned char* lds, const int mk_wid) {
;     ...
;           u16* qcol = qe + (g * 16) * QP + c; u16* kcol = ke + (g * 16) * QP + c; unsigned char* kdb = lds + L_KD + v_st(g * 16, c);
; #pragma unroll
;           for (int ii = 0; ii < 16; ++ii) { const float bb = bl[ii] + off;
;               const float qf = bf2f(qcol[ii * QP]), kf = bf2f(kcol[ii * QP]);
;               const float e = __builtin_amdgcn_exp2f(bb * 1.4426950408889634f), ker = kf * __builtin_amdgcn_rcpf(e);
;               qcol[ii * QP] = f2bf(qf * (0.088388347648318440f * e));
;               kcol[ii * QP] = f2bf(ker);
;               *(u16*)(kdb + v_st(ii, 0)) = f2bf(ker * dlc); } }
.Lscan_c2_nodl:
	v_mov_b32_e32 v71, 0xffff0000
	v_lshlrev_b32_e32 v218, 16, v128
	v_and_b32_e32 v219, v71, v128
	v_lshlrev_b32_e32 v220, 16, v100
	v_and_b32_e32 v221, v71, v100
	v_pk_mul_f32 v[218:219], v[170:171], v[218:219]
	v_pk_mul_f32 v[220:221], v[186:187], v[220:221]
	v_cvt_pk_bf16_f32 v224, v218, v219
	v_pk_mul_f32 v[222:223], v[92:93], v[220:221]
	v_cvt_pk_bf16_f32 v225, v220, v221
	ds_write_b32 v254, v224
	ds_write_b32 v254, v225 offset:17408
	v_cvt_pk_bf16_f32 v226, v222, v223
	ds_write_b32 v255, v226 offset:34816
	v_lshlrev_b32_e32 v228, 16, v129
	v_and_b32_e32 v229, v71, v129
	v_lshlrev_b32_e32 v230, 16, v101
	v_and_b32_e32 v231, v71, v101
	v_pk_mul_f32 v[228:229], v[172:173], v[228:229]
	v_pk_mul_f32 v[230:231], v[188:189], v[230:231]
	v_cvt_pk_bf16_f32 v234, v228, v229
	v_pk_mul_f32 v[232:233], v[92:93], v[230:231]
	v_cvt_pk_bf16_f32 v235, v230, v231
	ds_write_b32 v254, v234 offset:272
	ds_write_b32 v254, v235 offset:17680
	v_cvt_pk_bf16_f32 v236, v232, v233
	ds_write_b32 v255, v236 offset:34880
	v_lshlrev_b32_e32 v218, 16, v130
	v_and_b32_e32 v219, v71, v130
	v_lshlrev_b32_e32 v220, 16, v102
	v_and_b32_e32 v221, v71, v102
	v_pk_mul_f32 v[218:219], v[174:175], v[218:219]
	v_pk_mul_f32 v[220:221], v[190:191], v[220:221]
	v_cvt_pk_bf16_f32 v224, v218, v219
	v_pk_mul_f32 v[222:223], v[92:93], v[220:221]
	v_cvt_pk_bf16_f32 v225, v220, v221
	ds_write_b32 v254, v224 offset:544
	ds_write_b32 v254, v225 offset:17952
	v_cvt_pk_bf16_f32 v226, v222, v223
	ds_write_b32 v255, v226 offset:34944
	v_lshlrev_b32_e32 v228, 16, v131
	v_and_b32_e32 v229, v71, v131
	v_lshlrev_b32_e32 v230, 16, v103
	v_and_b32_e32 v231, v71, v103
	v_pk_mul_f32 v[228:229], v[176:177], v[228:229]
	v_pk_mul_f32 v[230:231], v[192:193], v[230:231]
	v_cvt_pk_bf16_f32 v234, v228, v229
	v_pk_mul_f32 v[232:233], v[92:93], v[230:231]
	v_cvt_pk_bf16_f32 v235, v230, v231
	ds_write_b32 v254, v234 offset:816
	ds_write_b32 v254, v235 offset:18224
	v_cvt_pk_bf16_f32 v236, v232, v233
	ds_write_b32 v255, v236 offset:35008
	v_lshlrev_b32_e32 v218, 16, v132
	v_and_b32_e32 v219, v71, v132
	v_lshlrev_b32_e32 v220, 16, v104
	v_and_b32_e32 v221, v71, v104
	v_pk_mul_f32 v[218:219], v[178:179], v[218:219]
	v_pk_mul_f32 v[220:221], v[194:195], v[220:221]
	v_cvt_pk_bf16_f32 v224, v218, v219
	v_pk_mul_f32 v[222:223], v[92:93], v[220:221]
	v_cvt_pk_bf16_f32 v225, v220, v221
	ds_write_b32 v254, v224 offset:1088
	ds_write_b32 v254, v225 offset:18496
	v_cvt_pk_bf16_f32 v226, v222, v223
	ds_write_b32 v255, v226 offset:36864
	v_lshlrev_b32_e32 v228, 16, v133
	v_and_b32_e32 v229, v71, v133
	v_lshlrev_b32_e32 v230, 16, v105
	v_and_b32_e32 v231, v71, v105
	v_pk_mul_f32 v[228:229], v[180:181], v[228:229]
	v_pk_mul_f32 v[230:231], v[196:197], v[230:231]
	v_cvt_pk_bf16_f32 v234, v228, v229
	v_pk_mul_f32 v[232:233], v[92:93], v[230:231]
	v_cvt_pk_bf16_f32 v235, v230, v231
	ds_write_b32 v254, v234 offset:1360
	ds_write_b32 v254, v235 offset:18768
	v_cvt_pk_bf16_f32 v236, v232, v233
	ds_write_b32 v255, v236 offset:36928
	v_lshlrev_b32_e32 v218, 16, v134
	v_and_b32_e32 v219, v71, v134
	v_lshlrev_b32_e32 v220, 16, v106
	v_and_b32_e32 v221, v71, v106
	v_pk_mul_f32 v[218:219], v[182:183], v[218:219]
	v_pk_mul_f32 v[220:221], v[198:199], v[220:221]
	v_cvt_pk_bf16_f32 v224, v218, v219
	v_pk_mul_f32 v[222:223], v[92:93], v[220:221]
	v_cvt_pk_bf16_f32 v225, v220, v221
	ds_write_b32 v254, v224 offset:1632
	ds_write_b32 v254, v225 offset:19040
	v_cvt_pk_bf16_f32 v226, v222, v223
	ds_write_b32 v255, v226 offset:36992
	v_lshlrev_b32_e32 v228, 16, v135
	v_and_b32_e32 v229, v71, v135
	v_lshlrev_b32_e32 v230, 16, v107
	v_and_b32_e32 v231, v71, v107
	v_pk_mul_f32 v[228:229], v[184:185], v[228:229]
	v_pk_mul_f32 v[230:231], v[200:201], v[230:231]
	v_cvt_pk_bf16_f32 v234, v228, v229
	v_pk_mul_f32 v[232:233], v[92:93], v[230:231]
	v_cvt_pk_bf16_f32 v235, v230, v231
	ds_write_b32 v254, v234 offset:1904
	ds_write_b32 v254, v235 offset:19312
	v_cvt_pk_bf16_f32 v236, v232, v233
	ds_write_b32 v255, v236 offset:37056
	s_waitcnt vmcnt(0)
	s_add_i32 s58, s5, 1
	s_cmp_eq_u32 s50, 3
	s_cbranch_scc1 .LBB0_435
	v_mbcnt_lo_u32_b32 v64, -1, 0
	v_mbcnt_hi_u32_b32 v64, -1, v64
	s_andn2_b64 vcc, exec, s[6:7]
	v_add_u32_e32 v70, s72, v64
	s_mov_b32 s34, s58
	s_cbranch_vccnz .LBB0_426
	s_cmp_gt_u32 s5, 2
	s_mov_b32 s34, s50
	s_cbranch_scc1 .LBB0_426
	s_sub_i32 s34, 2, s5
